# grid barrier: XCD leader no longer bumps the unused per-XCD release word nor waits for its ack
# baseline (speedup 1.0000x reference)
.LBB0_354:
	s_or_b64 exec, exec, s[6:7]
	s_waitcnt vmcnt(1)

.LBB0_1905:
	s_or_b64 exec, exec, s[4:5]
	s_waitcnt vmcnt(1)
